# spatial phase: LayerNorm gamma/beta rows for groups 2-4 loaded before the workgroup barrier (3 fewer serialized round trips per unit)
# speedup vs baseline: 1.0053x; 1.0019x over previous
.LBB0_261:
	s_or_b64 exec, exec, s[26:27]
	s_lshl_b32 s18, s45, 2
	v_lshl_add_u64 v[20:21], v[56:57], 0, s[18:19]
	v_lshl_add_u64 v[18:19], v[54:55], 0, s[18:19]
	global_load_dwordx4 v[170:173], v[20:21], off offset:32
	global_load_dwordx4 v[174:177], v[18:19], off offset:32
	global_load_dwordx4 v[178:181], v[18:19], off offset:48
	global_load_dwordx4 v[182:185], v[20:21], off offset:48
	global_load_dwordx4 v[186:189], v[20:21], off offset:64
	global_load_dwordx4 v[190:193], v[18:19], off offset:64
	global_load_dwordx4 v[194:197], v[18:19], off offset:80
	global_load_dwordx4 v[198:201], v[20:21], off offset:80
	global_load_dwordx4 v[202:205], v[20:21], off offset:96
	global_load_dwordx4 v[206:209], v[18:19], off offset:96
	global_load_dwordx4 v[210:213], v[18:19], off offset:112
	global_load_dwordx4 v[214:217], v[20:21], off offset:112
	s_waitcnt lgkmcnt(0)
	s_barrier
	v_lshl_add_u64 v[18:19], v[54:55], 0, s[18:19]
	global_load_dwordx4 v[22:25], v[20:21], off
	global_load_dwordx4 v[26:29], v[18:19], off
	global_load_dwordx4 v[30:33], v[18:19], off offset:16
	global_load_dwordx4 v[34:37], v[20:21], off offset:16
	ds_read_b64 v[16:17], v84 offset:34816
	s_waitcnt vmcnt(15)
	v_lshlrev_b32_e32 v38, 16, v0
	v_and_b32_e32 v39, 0xffff0000, v0
	v_lshlrev_b32_e32 v40, 16, v1
	v_and_b32_e32 v41, 0xffff0000, v1
	s_waitcnt lgkmcnt(0)
	v_sub_f32_e32 v38, v38, v16
	v_mul_f32_e32 v38, v17, v38
	v_sub_f32_e32 v39, v39, v16
	v_sub_f32_e32 v40, v40, v16
	v_mul_f32_e32 v39, v17, v39
	v_lshlrev_b32_e32 v42, 16, v2
	v_sub_f32_e32 v41, v41, v16
	v_mul_f32_e32 v40, v17, v40
	v_and_b32_e32 v43, 0xffff0000, v2
	v_sub_f32_e32 v42, v42, v16
	v_mul_f32_e32 v41, v17, v41
	v_lshlrev_b32_e32 v44, 16, v3
	v_and_b32_e32 v45, 0xffff0000, v3
	v_sub_f32_e32 v43, v43, v16
	v_mul_f32_e32 v42, v17, v42
	v_sub_f32_e32 v44, v44, v16
	v_sub_f32_e32 v45, v45, v16
	v_mul_f32_e32 v43, v17, v43
	v_mul_f32_e32 v44, v17, v44
	v_mul_f32_e32 v45, v17, v45
	s_waitcnt vmcnt(12)
	v_and_b32_e32 v46, 0xffff0000, v15
	v_sub_f32_e32 v46, v46, v16
	v_mul_f32_e32 v46, v17, v46
	s_add_i32 s31, s31, s35
	s_cmp_ge_i32 s31, s34
	s_cselect_b64 s[26:27], -1, 0
	s_and_b64 vcc, exec, s[26:27]
	s_waitcnt vmcnt(2)
	v_fma_f32 v22, v38, v26, v22
	v_cvt_pk_bf16_f32 v22, v22, v22
	v_fma_f32 v23, v39, v27, v23
	ds_write_b16 v87, v22
	v_cvt_pk_bf16_f32 v22, v23, v23
	v_fma_f32 v24, v40, v28, v24
	ds_write_b16 v87, v22 offset:272
	v_cvt_pk_bf16_f32 v22, v24, v24
	v_fmac_f32_e32 v25, v41, v29
	ds_write_b16 v87, v22 offset:544
	v_cvt_pk_bf16_f32 v22, v25, v25
	s_waitcnt vmcnt(0)
	v_fma_f32 v26, v42, v30, v34
	ds_write_b16 v87, v22 offset:816
	v_cvt_pk_bf16_f32 v22, v26, v26
	v_fma_f32 v27, v43, v31, v35
	ds_write_b16 v87, v22 offset:1088
	v_cvt_pk_bf16_f32 v22, v27, v27
	v_fma_f32 v28, v44, v32, v36
	v_fmac_f32_e32 v37, v45, v33
	ds_write_b16 v87, v22 offset:1360
	v_cvt_pk_bf16_f32 v22, v28, v28
	ds_write_b16 v87, v22 offset:1632
	v_cvt_pk_bf16_f32 v38, v37, v37
	v_mov_b64_e32 v[22:23], v[170:171]
	v_mov_b64_e32 v[24:25], v[172:173]
	v_mov_b64_e32 v[26:27], v[174:175]
	v_mov_b64_e32 v[28:29], v[176:177]
	v_mov_b64_e32 v[30:31], v[178:179]
	v_mov_b64_e32 v[32:33], v[180:181]
	v_mov_b64_e32 v[34:35], v[182:183]
	v_mov_b64_e32 v[36:37], v[184:185]
	v_lshlrev_b32_e32 v39, 16, v12
	v_sub_f32_e32 v39, v39, v16
	v_and_b32_e32 v40, 0xffff0000, v12
	v_mul_f32_e32 v39, v17, v39
	v_lshlrev_b32_e32 v41, 16, v13
	v_sub_f32_e32 v40, v40, v16
	v_and_b32_e32 v42, 0xffff0000, v13
	v_sub_f32_e32 v41, v41, v16
	v_mul_f32_e32 v40, v17, v40
	ds_write_b16 v87, v38 offset:1904
	v_lshlrev_b32_e32 v43, 16, v14
	v_sub_f32_e32 v42, v42, v16
	v_mul_f32_e32 v41, v17, v41
	v_and_b32_e32 v44, 0xffff0000, v14
	v_sub_f32_e32 v43, v43, v16
	v_mul_f32_e32 v42, v17, v42
	v_lshlrev_b32_e32 v45, 16, v15
	v_sub_f32_e32 v44, v44, v16
	v_mul_f32_e32 v43, v17, v43
	v_sub_f32_e32 v45, v45, v16
	v_mul_f32_e32 v44, v17, v44
	v_mul_f32_e32 v45, v17, v45
	s_waitcnt vmcnt(2)
	v_fma_f32 v22, v39, v26, v22
	v_cvt_pk_bf16_f32 v22, v22, v22
	v_fma_f32 v23, v40, v27, v23
	ds_write_b16 v88, v22
	v_cvt_pk_bf16_f32 v22, v23, v23
	v_fma_f32 v24, v41, v28, v24
	ds_write_b16 v87, v22 offset:2448
	v_cvt_pk_bf16_f32 v22, v24, v24
	v_fmac_f32_e32 v25, v42, v29
	ds_write_b16 v87, v22 offset:2720
	v_cvt_pk_bf16_f32 v22, v25, v25
	s_waitcnt vmcnt(0)
	v_fma_f32 v26, v43, v30, v34
	ds_write_b16 v87, v22 offset:2992
	v_cvt_pk_bf16_f32 v22, v26, v26
	v_fma_f32 v27, v44, v31, v35
	ds_write_b16 v87, v22 offset:3264
	v_cvt_pk_bf16_f32 v22, v27, v27
	v_fma_f32 v28, v45, v32, v36
	v_fmac_f32_e32 v37, v46, v33
	ds_write_b16 v87, v22 offset:3536
	v_cvt_pk_bf16_f32 v22, v28, v28
	ds_write_b16 v87, v22 offset:3808
	v_cvt_pk_bf16_f32 v38, v37, v37
	v_mov_b64_e32 v[22:23], v[186:187]
	v_mov_b64_e32 v[24:25], v[188:189]
	v_mov_b64_e32 v[26:27], v[190:191]
	v_mov_b64_e32 v[28:29], v[192:193]
	v_mov_b64_e32 v[30:31], v[194:195]
	v_mov_b64_e32 v[32:33], v[196:197]
	v_mov_b64_e32 v[34:35], v[198:199]
	v_mov_b64_e32 v[36:37], v[200:201]
	v_lshlrev_b32_e32 v39, 16, v8
	v_sub_f32_e32 v39, v39, v16
	v_and_b32_e32 v40, 0xffff0000, v8
	v_mul_f32_e32 v39, v17, v39
	v_lshlrev_b32_e32 v41, 16, v9
	v_sub_f32_e32 v40, v40, v16
	v_and_b32_e32 v42, 0xffff0000, v9
	v_sub_f32_e32 v41, v41, v16
	v_mul_f32_e32 v40, v17, v40
	ds_write_b16 v87, v38 offset:4080
	v_lshlrev_b32_e32 v43, 16, v10
	v_sub_f32_e32 v42, v42, v16
	v_mul_f32_e32 v41, v17, v41
	v_and_b32_e32 v44, 0xffff0000, v10
	v_sub_f32_e32 v43, v43, v16
	v_mul_f32_e32 v42, v17, v42
	v_lshlrev_b32_e32 v45, 16, v11
	v_sub_f32_e32 v44, v44, v16
	v_mul_f32_e32 v43, v17, v43
	v_and_b32_e32 v46, 0xffff0000, v11
	v_sub_f32_e32 v45, v45, v16
	v_mul_f32_e32 v44, v17, v44
	v_sub_f32_e32 v46, v46, v16
	v_mul_f32_e32 v45, v17, v45
	v_mul_f32_e32 v46, v17, v46
	v_and_b32_e32 v38, 0xffff0000, v5
	v_sub_f32_e32 v38, v38, v16
	v_mul_f32_e32 v38, v17, v38
	s_waitcnt vmcnt(2)
	v_fma_f32 v22, v39, v26, v22
	v_cvt_pk_bf16_f32 v22, v22, v22
	v_fma_f32 v23, v40, v27, v23
	ds_write_b16 v88, v22 offset:2176
	v_cvt_pk_bf16_f32 v22, v23, v23
	v_fma_f32 v24, v41, v28, v24
	ds_write_b16 v87, v22 offset:4624
	v_cvt_pk_bf16_f32 v22, v24, v24
	v_fmac_f32_e32 v25, v42, v29
	ds_write_b16 v87, v22 offset:4896
	v_cvt_pk_bf16_f32 v22, v25, v25
	s_waitcnt vmcnt(0)
	v_fma_f32 v26, v43, v30, v34
	ds_write_b16 v87, v22 offset:5168
	v_cvt_pk_bf16_f32 v22, v26, v26
	v_fma_f32 v27, v44, v31, v35
	ds_write_b16 v87, v22 offset:5440
	v_cvt_pk_bf16_f32 v22, v27, v27
	v_fma_f32 v28, v45, v32, v36
	ds_write_b16 v87, v22 offset:5712
	v_cvt_pk_bf16_f32 v22, v28, v28
	v_fmac_f32_e32 v37, v46, v33
	ds_write_b16 v87, v22 offset:5984
	v_cvt_pk_bf16_f32 v34, v37, v37
	v_mov_b64_e32 v[22:23], v[202:203]
	v_mov_b64_e32 v[24:25], v[204:205]
	v_mov_b64_e32 v[26:27], v[206:207]
	v_mov_b64_e32 v[28:29], v[208:209]
	v_mov_b64_e32 v[30:31], v[210:211]
	v_mov_b64_e32 v[32:33], v[212:213]
	s_nop 0
	v_mov_b64_e32 v[18:19], v[214:215]
	v_mov_b64_e32 v[20:21], v[216:217]
	v_lshlrev_b32_e32 v35, 16, v4
	v_and_b32_e32 v36, 0xffff0000, v4
	v_lshlrev_b32_e32 v37, 16, v5
	v_lshlrev_b32_e32 v39, 16, v6
	v_and_b32_e32 v40, 0xffff0000, v6
	v_lshlrev_b32_e32 v41, 16, v7
	v_and_b32_e32 v42, 0xffff0000, v7
	v_sub_f32_e32 v35, v35, v16
	v_sub_f32_e32 v36, v36, v16
	v_sub_f32_e32 v37, v37, v16
	v_sub_f32_e32 v39, v39, v16
	v_sub_f32_e32 v40, v40, v16
	v_sub_f32_e32 v41, v41, v16
	v_sub_f32_e32 v16, v42, v16
	v_mul_f32_e32 v35, v17, v35
	v_mul_f32_e32 v16, v17, v16
	v_mul_f32_e32 v36, v17, v36
	v_mul_f32_e32 v37, v17, v37
	v_mul_f32_e32 v39, v17, v39
	v_mul_f32_e32 v40, v17, v40
	v_mul_f32_e32 v41, v17, v41
	ds_write_b16 v87, v34 offset:6256
	s_waitcnt vmcnt(2)
	v_fma_f32 v17, v35, v26, v22
	v_fma_f32 v22, v36, v27, v23
	s_waitcnt vmcnt(0)
	v_fmac_f32_e32 v21, v16, v33
	v_cvt_pk_bf16_f32 v16, v17, v17
	ds_write_b16 v88, v16 offset:4352
	v_cvt_pk_bf16_f32 v16, v22, v22
	v_fma_f32 v23, v37, v28, v24
	ds_write_b16 v87, v16 offset:6800
	v_cvt_pk_bf16_f32 v16, v23, v23
	v_fmac_f32_e32 v25, v38, v29
	ds_write_b16 v87, v16 offset:7072
	v_cvt_pk_bf16_f32 v16, v25, v25
	v_fma_f32 v18, v39, v30, v18
	ds_write_b16 v87, v16 offset:7344
	v_cvt_pk_bf16_f32 v16, v18, v18
	v_fma_f32 v19, v40, v31, v19
	ds_write_b16 v87, v16 offset:7616
	v_cvt_pk_bf16_f32 v16, v19, v19
	v_fma_f32 v20, v41, v32, v20
	ds_write_b16 v87, v16 offset:7888
	v_cvt_pk_bf16_f32 v16, v20, v20
	ds_write_b16 v87, v16 offset:8160
	v_cvt_pk_bf16_f32 v16, v21, v21
	ds_write_b16 v87, v16 offset:8432
	s_cbranch_vccnz .LBB0_263
	s_lshl_b32 s18, s31, 3
	s_and_b32 s18, s18, 0xffffff80
	v_or_b32_e32 v0, s18, v82
	v_ashrrev_i32_e32 v1, 31, v0
	v_lshlrev_b64 v[0:1], 13, v[0:1]
	s_lshl_b32 s18, s31, 8
	v_lshl_add_u64 v[0:1], s[8:9], 0, v[0:1]
	s_and_b32 s18, s18, 0xf00
	v_lshl_add_u64 v[0:1], v[0:1], 0, s[18:19]
	v_lshl_add_u64 v[0:1], v[48:49], 1, v[0:1]
	v_lshl_add_u64 v[12:13], v[0:1], 0, s[24:25]
	v_add_co_u32_e32 v0, vcc, 0x1000, v0
	s_nop 1
	v_addc_co_u32_e32 v1, vcc, 0, v1, vcc
	global_load_dwordx4 v[0:3], v[0:1], off
	s_nop 0
	global_load_dwordx4 v[4:7], v[12:13], off offset:48
	global_load_dwordx4 v[8:11], v[12:13], off offset:32
	s_nop 0
	global_load_dwordx4 v[12:15], v[12:13], off offset:16
